# up-GEMM (P4/P11) tile epilogue replaced by a dedicated straight-line path: 64 cvt + 16 stores + halo, no per-row-group mode dispatch, no multiply by rs=1
# speedup vs baseline: 1.0138x; 1.0138x over previous
.Lup_epi:
	s_lshl_b32 s0, s67, 8
	s_add_i32 s0, s0, s19
	v_add_u32_e32 v134, s0, v182
	v_mov_b32_e32 v141, v182
	s_lshl_b32 s1, s90, 8
	v_add_lshl_u32 v138, v168, s1, 1
	v_mov_b32_e32 v139, 0
	v_mov_b32_e32 v136, 0x2c00
	v_mad_u64_u32 v[144:145], vcc, v134, v136, s[44:45]
	v_lshl_add_u64 v[144:145], v[138:139], 0, v[144:145]
	s_mov_b32 s0, 0x160000
	s_mov_b32 s1, 0
	v_lshl_add_u64 v[146:147], v[144:145], 0, s[0:1]
	s_mov_b32 s0, 0x2c000
	v_cvt_pk_bf16_f32 v224, v128, v129
	v_cvt_pk_bf16_f32 v225, v130, v131
	v_cvt_pk_bf16_f32 v226, v124, v125
	v_cvt_pk_bf16_f32 v227, v126, v127
	global_store_dwordx4 v[144:145], v[224:227], off
	v_cvt_pk_bf16_f32 v228, v120, v121
	v_cvt_pk_bf16_f32 v229, v122, v123
	v_cvt_pk_bf16_f32 v230, v116, v117
	v_cvt_pk_bf16_f32 v231, v118, v119
	global_store_dwordx4 v[144:145], v[228:231], off offset:256
	v_cvt_pk_bf16_f32 v232, v60, v61
	v_cvt_pk_bf16_f32 v233, v62, v63
	v_cvt_pk_bf16_f32 v234, v56, v57
	v_cvt_pk_bf16_f32 v235, v58, v59
	global_store_dwordx4 v[146:147], v[232:235], off
	v_cvt_pk_bf16_f32 v236, v52, v53
	v_cvt_pk_bf16_f32 v237, v54, v55
	v_cvt_pk_bf16_f32 v238, v48, v49
	v_cvt_pk_bf16_f32 v239, v50, v51
	global_store_dwordx4 v[146:147], v[236:239], off offset:256
	v_lshl_add_u64 v[144:145], v[144:145], 0, s[0:1]
	v_lshl_add_u64 v[146:147], v[146:147], 0, s[0:1]
	v_cvt_pk_bf16_f32 v240, v112, v113
	v_cvt_pk_bf16_f32 v241, v114, v115
	v_cvt_pk_bf16_f32 v242, v108, v109
	v_cvt_pk_bf16_f32 v243, v110, v111
	global_store_dwordx4 v[144:145], v[240:243], off
	v_cvt_pk_bf16_f32 v244, v104, v105
	v_cvt_pk_bf16_f32 v245, v106, v107
	v_cvt_pk_bf16_f32 v246, v100, v101
	v_cvt_pk_bf16_f32 v247, v102, v103
	global_store_dwordx4 v[144:145], v[244:247], off offset:256
	v_cvt_pk_bf16_f32 v224, v44, v45
	v_cvt_pk_bf16_f32 v225, v46, v47
	v_cvt_pk_bf16_f32 v226, v40, v41
	v_cvt_pk_bf16_f32 v227, v42, v43
	global_store_dwordx4 v[146:147], v[224:227], off
	v_cvt_pk_bf16_f32 v228, v36, v37
	v_cvt_pk_bf16_f32 v229, v38, v39
	v_cvt_pk_bf16_f32 v230, v32, v33
	v_cvt_pk_bf16_f32 v231, v34, v35
	global_store_dwordx4 v[146:147], v[228:231], off offset:256
	v_lshl_add_u64 v[144:145], v[144:145], 0, s[0:1]
	v_lshl_add_u64 v[146:147], v[146:147], 0, s[0:1]
	v_cvt_pk_bf16_f32 v232, v92, v93
	v_cvt_pk_bf16_f32 v233, v94, v95
	v_cvt_pk_bf16_f32 v234, v88, v89
	v_cvt_pk_bf16_f32 v235, v90, v91
	global_store_dwordx4 v[144:145], v[232:235], off
	v_cvt_pk_bf16_f32 v236, v84, v85
	v_cvt_pk_bf16_f32 v237, v86, v87
	v_cvt_pk_bf16_f32 v238, v80, v81
	v_cvt_pk_bf16_f32 v239, v82, v83
	global_store_dwordx4 v[144:145], v[236:239], off offset:256
	v_cvt_pk_bf16_f32 v240, v28, v29
	v_cvt_pk_bf16_f32 v241, v30, v31
	v_cvt_pk_bf16_f32 v242, v24, v25
	v_cvt_pk_bf16_f32 v243, v26, v27
	global_store_dwordx4 v[146:147], v[240:243], off
	v_cvt_pk_bf16_f32 v244, v20, v21
	v_cvt_pk_bf16_f32 v245, v22, v23
	v_cvt_pk_bf16_f32 v246, v16, v17
	v_cvt_pk_bf16_f32 v247, v18, v19
	global_store_dwordx4 v[146:147], v[244:247], off offset:256
	v_lshl_add_u64 v[144:145], v[144:145], 0, s[0:1]
	v_lshl_add_u64 v[146:147], v[146:147], 0, s[0:1]
	v_cvt_pk_bf16_f32 v170, v76, v77
	v_cvt_pk_bf16_f32 v171, v78, v79
	v_cvt_pk_bf16_f32 v172, v72, v73
	v_cvt_pk_bf16_f32 v173, v74, v75
	global_store_dwordx4 v[144:145], v[170:173], off
	v_cvt_pk_bf16_f32 v174, v68, v69
	v_cvt_pk_bf16_f32 v175, v70, v71
	v_cvt_pk_bf16_f32 v176, v64, v65
	v_cvt_pk_bf16_f32 v177, v66, v67
	global_store_dwordx4 v[144:145], v[174:177], off offset:256
	v_cvt_pk_bf16_f32 v188, v12, v13
	v_cvt_pk_bf16_f32 v189, v14, v15
	v_cvt_pk_bf16_f32 v190, v8, v9
	v_cvt_pk_bf16_f32 v191, v10, v11
	global_store_dwordx4 v[146:147], v[188:191], off
	v_cvt_pk_bf16_f32 v200, v4, v5
	v_cvt_pk_bf16_f32 v201, v6, v7
	v_cvt_pk_bf16_f32 v202, v0, v1
	v_cvt_pk_bf16_f32 v203, v2, v3
	global_store_dwordx4 v[146:147], v[200:203], off offset:256
	s_cmp_lg_u32 s19, 64
	s_cbranch_scc1 .Lup_done
	v_cmp_lt_u32_e64 s[6:7], 13, v141
	s_and_saveexec_b64 s[16:17], s[6:7]
	s_cbranch_execz .Lup_hdone
	s_lshl_b32 s4, s67, 2
	s_add_i32 s4, s4, -14
	v_add_u32_e32 v140, s4, v141
	s_add_u32 s4, s68, 0x19b0000
	s_addc_u32 s5, s69, 0
	v_mad_u64_u32 v[148:149], vcc, v140, v136, s[4:5]
	v_lshl_add_u64 v[148:149], v[138:139], 0, v[148:149]
	s_mov_b32 s4, 0x5800
	s_mov_b32 s5, 0
	v_lshl_add_u64 v[150:151], v[148:149], 0, s[4:5]
	global_store_dwordx4 v[148:149], v[170:173], off
	global_store_dwordx4 v[148:149], v[174:177], off offset:256
	global_store_dwordx4 v[150:151], v[188:191], off
	global_store_dwordx4 v[150:151], v[200:203], off offset:256
.Lup_hdone:
	s_or_b64 exec, exec, s[16:17]

.LBB0_439:
	s_cmp_eq_u32 s93, 2
	s_cbranch_scc1 .Lup_epi
	v_readlane_b32 s4, v255, 16
	v_readlane_b32 s5, v255, 17
	s_and_b64 vcc, exec, s[4:5]
	s_cbranch_vccz .LBB0_441
	s_lshl_b32 s4, s67, 8
	v_or_b32_e32 v183, s19, v182
	v_add_u32_e32 v174, s4, v183
	v_lshlrev_b32_e32 v132, 2, v166
	v_ashrrev_i32_e32 v133, 31, v132
	v_ashrrev_i32_e32 v175, 31, v174
	v_lshl_add_u64 v[132:133], v[132:133], 2, s[42:43]
	v_lshlrev_b64 v[134:135], 7, v[174:175]
	v_lshl_add_u64 v[136:137], v[132:133], 0, v[134:135]
	v_or_b32_e32 v134, 16, v174
	v_ashrrev_i32_e32 v135, 31, v134
	v_lshlrev_b64 v[134:135], 7, v[134:135]
	v_lshl_add_u64 v[154:155], v[132:133], 0, v[134:135]
	v_or_b32_e32 v134, 32, v174
	v_ashrrev_i32_e32 v135, 31, v134
	v_lshlrev_b64 v[134:135], 7, v[134:135]
	v_lshl_add_u64 v[180:181], v[132:133], 0, v[134:135]
	v_or_b32_e32 v134, 48, v174
	v_ashrrev_i32_e32 v135, 31, v134
	v_lshlrev_b64 v[134:135], 7, v[134:135]
	v_lshl_add_u64 v[184:185], v[132:133], 0, v[134:135]
	v_add_u32_e32 v134, 0x80, v174
	v_ashrrev_i32_e32 v135, 31, v134
	v_lshlrev_b64 v[134:135], 7, v[134:135]
	v_lshl_add_u64 v[200:201], v[132:133], 0, v[134:135]
	v_add_u32_e32 v134, 0x90, v174
	v_ashrrev_i32_e32 v135, 31, v134
	v_lshlrev_b64 v[134:135], 7, v[134:135]
	v_lshl_add_u64 v[188:189], v[132:133], 0, v[134:135]
	v_add_u32_e32 v134, 0xa0, v174
	v_ashrrev_i32_e32 v135, 31, v134
	v_lshlrev_b64 v[134:135], 7, v[134:135]
	v_lshl_add_u64 v[170:171], v[132:133], 0, v[134:135]
	v_add_u32_e32 v134, 0xb0, v174
	v_ashrrev_i32_e32 v135, 31, v134
	v_lshlrev_b64 v[134:135], 7, v[134:135]
	v_lshl_add_u64 v[146:147], v[132:133], 0, v[134:135]
	global_load_dwordx4 v[132:135], v[136:137], off offset:64
	s_nop 0
	global_load_dwordx4 v[136:139], v[136:137], off
	s_nop 0
	global_load_dwordx4 v[140:143], v[146:147], off offset:64
	s_nop 0
	global_load_dwordx4 v[146:149], v[146:147], off
	s_nop 0
	global_load_dwordx4 v[150:153], v[170:171], off offset:64
	s_nop 0
	global_load_dwordx4 v[170:173], v[170:171], off
	s_nop 0
	global_load_dwordx4 v[176:179], v[188:189], off offset:64
	s_nop 0
	global_load_dwordx4 v[188:191], v[188:189], off
	s_nop 0
	global_load_dwordx4 v[196:199], v[200:201], off offset:64
	s_nop 0
	global_load_dwordx4 v[200:203], v[200:201], off
	s_nop 0
	global_load_dwordx4 v[224:227], v[184:185], off offset:64
	global_load_dwordx4 v[228:231], v[184:185], off
	global_load_dwordx4 v[232:235], v[180:181], off offset:64
	global_load_dwordx4 v[236:239], v[180:181], off
	global_load_dwordx4 v[240:243], v[154:155], off offset:64
	global_load_dwordx4 v[244:247], v[154:155], off
	s_mov_b64 s[0:1], 0
	s_waitcnt vmcnt(0)
	s_nop 0
	v_add_f32_e32 v98, v136, v137
	v_add_f32_e32 v136, v138, v139
	v_add_f32_e32 v132, v132, v133
	v_add_f32_e32 v133, v134, v135
	v_add_f32_e32 v134, v244, v245
	v_add_f32_e32 v135, v246, v247
	v_add_f32_e32 v137, v240, v241
	v_add_f32_e32 v138, v242, v243
	v_add_f32_e32 v139, v236, v237
	v_add_f32_e32 v145, v238, v239
	v_add_f32_e32 v154, v232, v233
	v_add_f32_e32 v155, v234, v235
	v_add_f32_e32 v169, v228, v229
	v_add_f32_e32 v175, v230, v231
	v_add_f32_e32 v180, v224, v225
	v_add_f32_e32 v181, v226, v227
	v_add_f32_e32 v98, v98, v136
	v_add_f32_e32 v132, v132, v133
	v_add_f32_e32 v133, v134, v135
	v_add_f32_e32 v134, v137, v138
	v_add_f32_e32 v135, v139, v145
	v_add_f32_e32 v136, v154, v155
	v_add_f32_e32 v137, v169, v175
	v_add_f32_e32 v138, v180, v181
	v_add_f32_e32 v188, v188, v189
	v_add_f32_e32 v98, v98, v132
	v_add_f32_e32 v132, v133, v134
	v_add_f32_e32 v133, v135, v136
	v_add_f32_e32 v134, v137, v138
	v_add_f32_e32 v136, v190, v191
	v_add_f32_e32 v137, v176, v177
	v_add_f32_e32 v138, v178, v179
	v_add_f32_e32 v184, v200, v201
	v_add_f32_e32 v185, v202, v203
	v_add_f32_e32 v193, v196, v197
	v_add_f32_e32 v196, v198, v199
	v_add_f32_e32 v136, v188, v136
	v_add_f32_e32 v137, v137, v138
	v_add_f32_e32 v139, v184, v185
	v_add_f32_e32 v145, v193, v196
	v_add_f32_e32 v136, v136, v137
	v_add_f32_e32 v137, v170, v171
	v_add_f32_e32 v138, v172, v173
	v_add_f32_e32 v135, v139, v145
	v_add_f32_e32 v137, v137, v138
	v_add_f32_e32 v138, v150, v151
	v_add_f32_e32 v139, v152, v153
	v_add_f32_e32 v138, v138, v139
	v_add_f32_e32 v137, v137, v138
	v_add_f32_e32 v138, v146, v147
	v_add_f32_e32 v139, v148, v149
	v_and_b32_e32 v145, 64, v214
	v_add_f32_e32 v138, v138, v139
	v_xor_b32_e32 v139, 16, v214
	v_add_u32_e32 v145, 64, v145
	v_cmp_lt_i32_e32 vcc, v139, v145
	v_add_f32_e32 v140, v140, v141
	v_add_f32_e32 v141, v142, v143
	v_cndmask_b32_e32 v139, v214, v139, vcc
	v_lshlrev_b32_e32 v139, 2, v139
	v_add_f32_e32 v140, v140, v141
	ds_bpermute_b32 v141, v139, v133
	ds_bpermute_b32 v146, v139, v98
	v_add_f32_e32 v138, v138, v140
	ds_bpermute_b32 v140, v139, v132
	ds_bpermute_b32 v142, v139, v134
	ds_bpermute_b32 v143, v139, v135
	s_waitcnt lgkmcnt(4)
	v_add_f32_e32 v133, v133, v141
	v_xor_b32_e32 v141, 32, v214
	v_cmp_lt_i32_e32 vcc, v141, v145
	s_waitcnt lgkmcnt(3)
	v_add_f32_e32 v98, v98, v146
	ds_bpermute_b32 v146, v139, v136
	s_waitcnt lgkmcnt(3)
	v_add_f32_e32 v132, v132, v140
	ds_bpermute_b32 v140, v139, v137
	ds_bpermute_b32 v139, v139, v138
	v_cndmask_b32_e32 v141, v214, v141, vcc
	v_lshlrev_b32_e32 v141, 2, v141
	s_waitcnt lgkmcnt(4)
	v_add_f32_e32 v134, v134, v142
	ds_bpermute_b32 v142, v141, v98
	s_waitcnt lgkmcnt(4)
	v_add_f32_e32 v135, v135, v143
	ds_bpermute_b32 v143, v141, v132
	ds_bpermute_b32 v145, v141, v133
	s_waitcnt lgkmcnt(3)
	v_add_f32_e32 v138, v138, v139
	ds_bpermute_b32 v139, v141, v134
	v_add_f32_e32 v136, v136, v146
	v_add_f32_e32 v137, v137, v140
	ds_bpermute_b32 v140, v141, v135
	s_waitcnt lgkmcnt(4)
	v_add_f32_e32 v98, v98, v142
	ds_bpermute_b32 v142, v141, v136
	s_waitcnt lgkmcnt(4)
	v_add_f32_e32 v132, v132, v143
	ds_bpermute_b32 v143, v141, v137
	v_fmamk_f32 v98, v98, 0x3a800000, v206
	s_waitcnt lgkmcnt(4)
	v_add_f32_e32 v133, v133, v145
	ds_bpermute_b32 v141, v141, v138
	v_rsq_f32_e32 v172, v98
	v_fmamk_f32 v98, v132, 0x3a800000, v206
	s_waitcnt lgkmcnt(4)
	v_add_f32_e32 v134, v134, v139
	v_rsq_f32_e32 v173, v98
	v_fmamk_f32 v98, v133, 0x3a800000, v206
	s_waitcnt lgkmcnt(3)
	v_add_f32_e32 v135, v135, v140
	v_rsq_f32_e32 v170, v98
	v_fmamk_f32 v98, v134, 0x3a800000, v206
	s_waitcnt lgkmcnt(2)
	v_add_f32_e32 v136, v136, v142
	v_rsq_f32_e32 v171, v98
	v_fmamk_f32 v98, v135, 0x3a800000, v206
	s_waitcnt lgkmcnt(1)
	v_add_f32_e32 v137, v137, v143
	v_rsq_f32_e32 v154, v98
	v_fmamk_f32 v98, v136, 0x3a800000, v206
	s_waitcnt lgkmcnt(0)
	v_add_f32_e32 v138, v138, v141
	v_rsq_f32_e32 v155, v98
	v_fmamk_f32 v98, v137, 0x3a800000, v206
	v_rsq_f32_e32 v142, v98
	v_fmamk_f32 v98, v138, 0x3a800000, v206
	v_rsq_f32_e32 v143, v98
	v_mov_b32_e32 v184, s4
